# HGRN: producer score LDS reads hoisted and overlapped with global loads; both value-halves of a chain placed on one XCD
# speedup vs baseline: 1.0182x; 1.0056x over previous
.LBB0_146:
	v_mov_b32_e32 v36, v188
	s_nop 0
	v_readfirstlane_b32 s0, v36
	s_ashr_i32 s12, s0, 6
	s_and_b32 s1, s3, 0x70
	s_and_b32 s14, s3, 7
	s_lshl_b32 s14, s14, 1
	s_or_b32 s1, s1, s14
	s_bfe_u32 s14, s3, 0x10003
	s_or_b32 s1, s1, s14
	s_lshl_b32 s0, s1, 6
	s_and_b32 s11, s0, 0x780
	s_and_b32 s10, s0, 64
	s_cmp_lt_u32 s1, 64
	s_cselect_b64 s[36:37], -1, 0
	s_lshl_b32 s0, s1, 8
	s_and_b32 s4, s0, 0x2000
	v_and_b32_e32 v110, 15, v36
	v_lshrrev_b32_e32 v104, 4, v36
	v_bfe_u32 v106, v36, 4, 2
	s_cmp_lt_i32 s12, 4
	s_mov_b64 s[0:1], -1
	s_cbranch_scc0 .LBB0_153
	s_and_b64 s[14:15], s[36:37], exec
	s_cselect_b32 s1, 0, 0x4000000
	s_add_u32 s1, s88, s1
	s_addc_u32 s13, s89, 0
	s_lshl_b32 s14, s11, 1
	s_add_u32 s1, s1, s14
	s_addc_u32 s13, s13, 0
	s_lshl_b32 s14, s10, 1
	s_add_u32 s1, s1, s14
	s_addc_u32 s13, s13, 0
	s_lshl_b32 s14, s12, 4
	s_ashr_i32 s15, s14, 31
	s_lshl_b64 s[14:15], s[14:15], 1
	s_waitcnt lgkmcnt(0)
	v_lshlrev_b32_e32 v2, 3, v106
	s_add_u32 s14, s1, s14
	s_movk_i32 s1, 0x90
	v_mad_u32_u24 v3, v110, s1, v2
	v_readlane_b32 s1, v247, 63
	s_mulk_i32 s12, 0x900
	s_addc_u32 s15, s13, s15
	v_add_u32_e32 v40, s1, v3
	s_add_i32 s1, s12, 0
	v_cmp_gt_u32_e32 vcc, 2, v106
	s_add_i32 s1, s1, 0xd000
	v_add_u32_e32 v41, s1, v3
	v_cndmask_b32_e64 v0, v195, 0, vcc
	s_movk_i32 s1, 0x110
	v_lshlrev_b32_e32 v1, 3, v104
	v_lshlrev_b32_e32 v96, 1, v110
	v_mad_u32_u24 v0, v110, s1, v0
	v_lshl_add_u64 v[32:33], s[14:15], 0, v[96:97]
	v_mul_u32_u24_e32 v3, 0x110, v110
	v_and_or_b32 v0, v1, 8, v0
	v_readlane_b32 s1, v248, 0
	v_mov_b32_e32 v96, v97
	v_lshlrev_b32_e32 v37, 2, v106
	v_add_u32_e32 v42, s1, v0
	v_add3_u32 v43, v3, v2, 0
	v_mov_b32_e32 v98, v97
	s_waitcnt vmcnt(0)
	v_mov_b32_e32 v99, v97
	v_mov_b64_e32 v[0:1], v[96:97]
	v_mov_b64_e32 v[4:5], v[96:97]
	v_mov_b64_e32 v[8:9], v[96:97]
	v_mov_b64_e32 v[12:13], v[96:97]
	v_mov_b64_e32 v[16:17], v[96:97]
	v_mov_b64_e32 v[20:21], v[96:97]
	v_mov_b64_e32 v[24:25], v[96:97]
	v_mov_b64_e32 v[28:29], v[96:97]
	v_mov_b64_e32 v[2:3], v[98:99]
	v_mov_b64_e32 v[6:7], v[98:99]
	v_mov_b64_e32 v[10:11], v[98:99]
	v_mov_b64_e32 v[14:15], v[98:99]
	v_mov_b64_e32 v[18:19], v[98:99]
	v_mov_b64_e32 v[22:23], v[98:99]
	v_mov_b64_e32 v[26:27], v[98:99]
	v_mov_b64_e32 v[30:31], v[98:99]
	v_lshl_add_u32 v38, v106, 4, s73
	v_xor_b32_e32 v39, 0x203c, v37
	s_lshl_b32 s1, s4, 12
	s_add_u32 s14, s14, s1
	s_addc_u32 s15, s15, 0
	s_mov_b32 s13, 0x10000
	s_cmp_lg_u64 s[36:37], 0
	s_cselect_b32 s13, s13, 0xffff0000
	s_ashr_i32 s1, s13, 4
	v_add_u32_e32 v58, 0xffffffc3, v39
	v_cndmask_b32_e64 v58, v58, v37, s[36:37]
	v_lshlrev_b32_e32 v58, 12, v58
	v_lshl_add_u32 v160, v110, 1, v58
	v_add_u32_e32 v161, s1, v160
	v_add_u32_e32 v162, s1, v161
	v_add_u32_e32 v163, s1, v162
	s_lshl_b32 s1, s11, 1
	s_add_u32 s16, s76, s1
	s_addc_u32 s17, s77, 0
	s_lshl_b32 s18, s13, 2
	v_and_b32_e32 v169, 63, v36
	v_lshrrev_b32_e32 v170, 6, v36
	v_lshlrev_b32_e32 v170, 4, v170
	v_bfe_u32 v171, v169, 1, 4
	v_add_u32_e32 v171, v170, v171
	v_and_b32_e32 v172, 15, v169
	v_add_u32_e32 v172, v170, v172
	v_sub_u32_e32 v170, 0x1fff, v171
	v_cndmask_b32_e64 v171, v170, v171, s[36:37]
	v_sub_u32_e32 v170, 0x1fff, v172
	v_cndmask_b32_e64 v172, v170, v172, s[36:37]
	v_add_u32_e32 v171, s4, v171
	v_add_u32_e32 v172, s4, v172
	v_lshlrev_b32_e32 v171, 12, v171
	v_lshlrev_b32_e32 v172, 12, v172
	v_and_b32_e32 v170, 1, v169
	v_lshl_or_b32 v171, v170, 7, v171
	s_mov_b32 s1, 0x8000000
	s_cmp_lg_u64 s[36:37], 0
	s_cselect_b32 s1, s1, 0xc000000
	v_mov_b32_e32 v170, s1
	v_cmp_gt_u32_e32 vcc, 32, v169
	s_nop 1
	v_cndmask_b32_e32 v170, 0, v170, vcc
	v_add_u32_e32 v171, v170, v171
	s_lshl_b32 s1, s10, 1
	s_add_u32 s1, s1, 0x4000000
	v_add_u32_e32 v172, s1, v172
	s_mul_i32 s1, s18, 5
	v_add_u32_e32 v171, s1, v171
	v_add_u32_e32 v172, s1, v172
	s_mov_b32 s0, 1
	s_barrier

.LBB0_223:
	s_or_b64 exec, exec, s[14:15]
	ds_write_b64 v134, v[2:3] offset:62464
	v_add_u32_e32 v157, v101, v102
	ds_read_b128 v[4:7], v157 offset:17408
	ds_read_b128 v[8:11], v157
	ds_read_b128 v[12:15], v157 offset:17472
	ds_read_b128 v[16:19], v157 offset:64
	ds_read_b128 v[20:23], v157 offset:17536
	ds_read_b128 v[24:27], v157 offset:128
	ds_read_b128 v[164:167], v157 offset:17600
	ds_read_b128 v[168:171], v157 offset:192
	s_cmpk_gt_u32 s18, 0x7d
	s_cselect_b64 s[14:15], -1, 0
	s_and_b64 vcc, exec, s[14:15]
	s_cbranch_vccnz .Lh3_skipA
	v_add_u32_e32 v0, 0xffffffb1, v110
	v_add_u32_e32 v1, 0x4f, v111
	v_cndmask_b32_e64 v0, v1, v0, s[36:37]
	s_and_b64 s[16:17], s[36:37], exec
	s_movk_i32 s16, 0x1000
	s_cselect_b32 s16, s16, 0xfffff000
	v_add_u32_e32 v0, s4, v0
	v_lshlrev_b32_e32 v0, 12, v0
	v_lshl_or_b32 v0, v28, 1, v0
	global_load_dword v29, v0, s[12:13]
	global_load_dword v30, v0, s[0:1]
	global_load_dword v31, v0, s[10:11]
	v_add_u32_e32 v0, s16, v0
	global_load_dword v33, v0, s[12:13]
	global_load_dword v34, v0, s[0:1]
	global_load_dword v32, v0, s[10:11]
	v_add_u32_e32 v0, s16, v0
	global_load_dword v36, v0, s[12:13]
	global_load_dword v37, v0, s[0:1]
	global_load_dword v35, v0, s[10:11]
	v_add_u32_e32 v0, s16, v0
	global_load_dword v39, v0, s[12:13]
	global_load_dword v40, v0, s[0:1]
	global_load_dword v38, v0, s[10:11]
	v_add_u32_e32 v0, s16, v0
	global_load_dword v42, v0, s[12:13]
	global_load_dword v43, v0, s[0:1]
	global_load_dword v41, v0, s[10:11]
	v_add_u32_e32 v0, s16, v0
	global_load_dword v45, v0, s[12:13]
	global_load_dword v46, v0, s[0:1]
	global_load_dword v44, v0, s[10:11]
	v_add_u32_e32 v0, s16, v0
	global_load_dword v48, v0, s[12:13]
	global_load_dword v49, v0, s[0:1]
	global_load_dword v47, v0, s[10:11]
	v_add_u32_e32 v0, s16, v0
	global_load_dword v51, v0, s[12:13]
	global_load_dword v52, v0, s[0:1]
	global_load_dword v50, v0, s[10:11]
	v_add_u32_e32 v0, s16, v0
	global_load_dword v57, v0, s[12:13]
	global_load_dword v59, v0, s[0:1]
	global_load_dword v56, v0, s[10:11]
	v_add_u32_e32 v0, s16, v0
	global_load_dword v63, v0, s[12:13]
	global_load_dword v64, v0, s[0:1]
	global_load_dword v62, v0, s[10:11]
	v_add_u32_e32 v0, s16, v0
	global_load_dword v69, v0, s[12:13]
	global_load_dword v71, v0, s[0:1]
	global_load_dword v68, v0, s[10:11]
	v_add_u32_e32 v0, s16, v0
	global_load_dword v75, v0, s[12:13]
	global_load_dword v76, v0, s[0:1]
	global_load_dword v74, v0, s[10:11]
	v_add_u32_e32 v0, s16, v0
	global_load_dword v81, v0, s[12:13]
	global_load_dword v83, v0, s[0:1]
	global_load_dword v80, v0, s[10:11]
	v_add_u32_e32 v0, s16, v0
	global_load_dword v87, v0, s[12:13]
	global_load_dword v88, v0, s[0:1]
	global_load_dword v86, v0, s[10:11]
	v_add_u32_e32 v0, s16, v0
	global_load_dword v93, v0, s[12:13]
	global_load_dword v95, v0, s[0:1]
	global_load_dword v92, v0, s[10:11]
	v_add_u32_e32 v0, s16, v0
	global_load_dword v107, v0, s[12:13]
	global_load_dword v108, v0, s[0:1]
	global_load_dword v105, v0, s[10:11]
	s_branch .Lh3_joinA

.Lh3_joinA:
	s_waitcnt lgkmcnt(6)
	v_mfma_f32_16x16x32_bf16 v[0:3], v[4:7], v[8:11], 0
	s_waitcnt lgkmcnt(4)
	v_mfma_f32_16x16x32_bf16 v[0:3], v[12:15], v[16:19], v[0:3]
	s_waitcnt lgkmcnt(2)
	v_mfma_f32_16x16x32_bf16 v[0:3], v[20:23], v[24:27], v[0:3]
	s_waitcnt lgkmcnt(0)
	v_mfma_f32_16x16x32_bf16 v[0:3], v[164:167], v[168:171], v[0:3]
	s_nop 7
	v_cndmask_b32_e64 v0, v0, 0, s[40:41]
	v_cndmask_b32_e64 v1, 0, v1, s[42:43]
	v_cndmask_b32_e64 v2, v2, 0, s[44:45]
	v_cndmask_b32_e64 v3, v3, 0, s[46:47]
	v_cvt_pk_bf16_f32 v0, v0, v1
	v_cvt_pk_bf16_f32 v1, v2, v3
	ds_write_b64 v135, v[0:1] offset:256

.LBB0_259:
	s_or_b64 exec, exec, s[16:17]
	v_add_u32_e32 v0, 0x1f000, v134
	ds_write_b64 v0, v[2:3]
	ds_read_b128 v[4:7], v133
	ds_read_b128 v[8:11], v157 offset:64512
	ds_read_b128 v[12:15], v133 offset:64
	ds_read_b128 v[16:19], v157 offset:64576
	ds_read_b128 v[20:23], v133 offset:128
	ds_read_b128 v[24:27], v157 offset:64640
	ds_read_b128 v[164:167], v133 offset:192
	ds_read_b128 v[168:171], v157 offset:64704
	s_cmpk_gt_u32 s18, 0x7c
	s_cbranch_scc1 .Lh3_skipB
	v_add_u32_e32 v0, -15, v110
	v_add_u32_e32 v1, 15, v111
	v_cndmask_b32_e64 v0, v1, v0, s[36:37]
	s_and_b64 s[16:17], s[36:37], exec
	s_movk_i32 s16, 0x1000
	s_cselect_b32 s16, s16, 0xfffff000
	v_add_u32_e32 v0, s4, v0
	v_lshlrev_b32_e32 v0, 12, v0
	v_lshl_or_b32 v0, v28, 1, v0
	global_load_dword v54, v0, s[12:13]
	global_load_dword v55, v0, s[0:1]
	global_load_dword v53, v0, s[10:11]
	v_add_u32_e32 v0, s16, v0
	global_load_dword v60, v0, s[12:13]
	global_load_dword v61, v0, s[0:1]
	global_load_dword v58, v0, s[10:11]
	v_add_u32_e32 v0, s16, v0
	global_load_dword v66, v0, s[12:13]
	global_load_dword v67, v0, s[0:1]
	global_load_dword v65, v0, s[10:11]
	v_add_u32_e32 v0, s16, v0
	global_load_dword v72, v0, s[12:13]
	global_load_dword v73, v0, s[0:1]
	global_load_dword v70, v0, s[10:11]
	v_add_u32_e32 v0, s16, v0
	global_load_dword v78, v0, s[12:13]
	global_load_dword v79, v0, s[0:1]
	global_load_dword v77, v0, s[10:11]
	v_add_u32_e32 v0, s16, v0
	global_load_dword v84, v0, s[12:13]
	global_load_dword v85, v0, s[0:1]
	global_load_dword v82, v0, s[10:11]
	v_add_u32_e32 v0, s16, v0
	global_load_dword v90, v0, s[12:13]
	global_load_dword v91, v0, s[0:1]
	global_load_dword v89, v0, s[10:11]
	v_add_u32_e32 v0, s16, v0
	global_load_dword v99, v0, s[12:13]
	global_load_dword v103, v0, s[0:1]
	global_load_dword v94, v0, s[10:11]
	v_add_u32_e32 v0, s16, v0
	global_load_dword v121, v0, s[12:13]
	global_load_dword v131, v0, s[0:1]
	global_load_dword v109, v0, s[10:11]
	v_add_u32_e32 v0, s16, v0
	global_load_dword v137, v0, s[12:13]
	global_load_dword v138, v0, s[0:1]
	global_load_dword v136, v0, s[10:11]
	v_add_u32_e32 v0, s16, v0
	global_load_dword v140, v0, s[12:13]
	global_load_dword v141, v0, s[0:1]
	global_load_dword v139, v0, s[10:11]
	v_add_u32_e32 v0, s16, v0
	global_load_dword v143, v0, s[12:13]
	global_load_dword v144, v0, s[0:1]
	global_load_dword v142, v0, s[10:11]
	v_add_u32_e32 v0, s16, v0
	global_load_dword v146, v0, s[12:13]
	global_load_dword v147, v0, s[0:1]
	global_load_dword v145, v0, s[10:11]
	v_add_u32_e32 v0, s16, v0
	global_load_dword v149, v0, s[12:13]
	global_load_dword v150, v0, s[0:1]
	global_load_dword v148, v0, s[10:11]
	v_add_u32_e32 v0, s16, v0
	global_load_dword v152, v0, s[12:13]
	global_load_dword v153, v0, s[0:1]
	global_load_dword v151, v0, s[10:11]
	v_add_u32_e32 v0, s16, v0
	global_load_dword v155, v0, s[12:13]
	global_load_dword v156, v0, s[0:1]
	global_load_dword v154, v0, s[10:11]
	s_branch .Lh3_joinB

.Lh3_joinB:
	s_waitcnt lgkmcnt(6)
	v_mfma_f32_16x16x32_bf16 v[0:3], v[4:7], v[8:11], 0
	s_waitcnt lgkmcnt(4)
	v_mfma_f32_16x16x32_bf16 v[0:3], v[12:15], v[16:19], v[0:3]
	s_waitcnt lgkmcnt(2)
	v_mfma_f32_16x16x32_bf16 v[0:3], v[20:23], v[24:27], v[0:3]
	s_waitcnt lgkmcnt(0)
	v_mfma_f32_16x16x32_bf16 v[0:3], v[164:167], v[168:171], v[0:3]
	s_nop 7
	v_cndmask_b32_e64 v0, v0, 0, s[40:41]
	v_cndmask_b32_e64 v1, 0, v1, s[42:43]
	v_cndmask_b32_e64 v2, v2, 0, s[44:45]
	v_cndmask_b32_e64 v3, v3, 0, s[46:47]
	v_cvt_pk_bf16_f32 v0, v0, v1
	v_cvt_pk_bf16_f32 v1, v2, v3
	ds_write_b64 v135, v[0:1] offset:64768
	s_branch .LBB0_220
